# dense-down epilogue: each row step's 5 loads issued during the previous step (dead 18-register buffer), no longer behind the previous step's store acks; counted waits
# speedup vs baseline: 1.0035x; 1.0035x over previous
.LBB0_1077:
	v_mov_b32_e32 v116, v0
	s_lshl_b32 s5, s62, 8
	v_lshrrev_b32_e32 v114, 1, v116
	s_lshl_b32 s4, s61, 8
	v_and_or_b32 v114, v114, 24, s5
	s_add_i32 s4, s4, s84
	v_or_b32_e32 v114, s85, v114
	v_ashrrev_i32_e32 v115, 31, v114
	v_and_or_b32 v174, v116, 15, s4
	v_lshlrev_b64 v[172:173], 2, v[114:115]
	v_ashrrev_i32_e32 v175, 31, v174
	v_lshlrev_b32_e32 v114, 1, v174
	v_ashrrev_i32_e32 v115, 31, v114
	v_lshlrev_b64 v[116:117], 13, v[174:175]
	v_lshl_add_u64 v[114:115], v[114:115], 2, s[22:23]
	v_lshl_add_u64 v[116:117], s[20:21], 0, v[116:117]
	v_readlane_b32 s48, v254, 30
	v_lshl_add_u64 v[196:197], v[116:117], 0, v[172:173]
	global_load_dwordx2 v[198:199], v[114:115], off
	global_load_dwordx4 v[180:183], v[196:197], off
	global_load_dwordx4 v[184:187], v[196:197], off offset:16
	global_load_dwordx4 v[188:191], v[196:197], off offset:512
	global_load_dwordx4 v[192:195], v[196:197], off offset:528
	v_readlane_b32 s52, v254, 34
	v_readlane_b32 s53, v254, 35
	v_readlane_b32 s54, v254, 36
	v_readlane_b32 s55, v254, 37
	v_lshl_add_u64 v[122:123], s[52:53], 0, v[172:173]
	v_or_b32_e32 v200, 16, v174
	v_lshl_add_u64 v[142:143], s[54:55], 0, v[172:173]
	global_load_dwordx4 v[118:121], v[142:143], off
	global_load_dwordx4 v[130:133], v[122:123], off
	global_load_dwordx4 v[114:117], v[122:123], off offset:16
	global_load_dwordx4 v[134:137], v[142:143], off offset:16
	global_load_dwordx4 v[126:129], v[142:143], off offset:512
	global_load_dwordx4 v[138:141], v[122:123], off offset:512
	s_nop 0
	global_load_dwordx4 v[122:125], v[122:123], off offset:528
	s_nop 0
	global_load_dwordx4 v[142:145], v[142:143], off offset:528
	v_ashrrev_i32_e32 v201, 31, v200
	v_lshlrev_b32_e32 v202, 1, v200
	v_ashrrev_i32_e32 v203, 31, v202
	v_lshlrev_b64 v[200:201], 13, v[200:201]
	v_lshl_add_u64 v[202:203], v[202:203], 2, s[22:23]
	v_lshl_add_u64 v[200:201], s[20:21], 0, v[200:201]
	v_lshl_add_u64 v[200:201], v[200:201], 0, v[172:173]
	s_and_b64 vcc, exec, s[6:7]
	s_mov_b64 s[4:5], -1
	v_readlane_b32 s49, v254, 31
	v_readlane_b32 s50, v254, 32
	v_readlane_b32 s51, v254, 33
	v_readlane_b32 s56, v254, 38
	v_readlane_b32 s57, v254, 39
	v_readlane_b32 s58, v254, 40
	v_readlane_b32 s59, v254, 41
	v_readlane_b32 s60, v254, 42
	v_readlane_b32 s61, v254, 43
	v_readlane_b32 s62, v254, 44
	v_readlane_b32 s63, v254, 45
	global_load_dwordx2 v[238:239], v[202:203], off
	global_load_dwordx4 v[204:207], v[200:201], off
	global_load_dwordx4 v[208:211], v[200:201], off offset:16
	global_load_dwordx4 v[212:215], v[200:201], off offset:512
	global_load_dwordx4 v[216:219], v[200:201], off offset:528
	s_waitcnt vmcnt(5)
	v_sub_f32_e32 v183, v183, v198
	v_sub_f32_e32 v182, v182, v198
	v_sub_f32_e32 v181, v181, v198
	v_sub_f32_e32 v180, v180, v198
	v_sub_f32_e32 v187, v187, v198
	v_sub_f32_e32 v186, v186, v198
	v_sub_f32_e32 v185, v185, v198
	v_sub_f32_e32 v184, v184, v198
	v_sub_f32_e32 v191, v191, v198
	v_sub_f32_e32 v190, v190, v198
	v_sub_f32_e32 v189, v189, v198
	v_sub_f32_e32 v188, v188, v198
	v_sub_f32_e32 v195, v195, v198
	v_sub_f32_e32 v194, v194, v198
	v_sub_f32_e32 v193, v193, v198
	v_sub_f32_e32 v192, v192, v198
	v_pk_mul_f32 v[180:181], v[198:199], v[180:181] op_sel:[1,0]
	v_pk_mul_f32 v[182:183], v[198:199], v[182:183] op_sel:[1,0]
	v_pk_mul_f32 v[184:185], v[198:199], v[184:185] op_sel:[1,0]
	v_pk_mul_f32 v[186:187], v[198:199], v[186:187] op_sel:[1,0]
	v_pk_mul_f32 v[188:189], v[198:199], v[188:189] op_sel:[1,0]
	v_pk_mul_f32 v[190:191], v[198:199], v[190:191] op_sel:[1,0]
	v_pk_mul_f32 v[192:193], v[198:199], v[192:193] op_sel:[1,0]
	v_pk_mul_f32 v[194:195], v[198:199], v[194:195] op_sel:[1,0]
	v_pk_fma_f32 v[182:183], v[132:133], v[182:183], v[120:121]
	v_pk_fma_f32 v[180:181], v[130:131], v[180:181], v[118:119]
	v_pk_fma_f32 v[186:187], v[116:117], v[186:187], v[136:137]
	v_pk_fma_f32 v[184:185], v[114:115], v[184:185], v[134:135]
	v_pk_fma_f32 v[190:191], v[140:141], v[190:191], v[128:129]
	v_pk_fma_f32 v[188:189], v[138:139], v[188:189], v[126:127]
	v_pk_fma_f32 v[194:195], v[124:125], v[194:195], v[144:145]
	v_pk_fma_f32 v[192:193], v[122:123], v[192:193], v[142:143]
	v_pk_fma_f32 v[160:161], v[182:183], s[44:45], v[160:161] op_sel_hi:[1,0,1]
	v_pk_fma_f32 v[158:159], v[180:181], s[44:45], v[158:159] op_sel_hi:[1,0,1]
	v_pk_fma_f32 v[156:157], v[186:187], s[44:45], v[156:157] op_sel_hi:[1,0,1]
	v_pk_fma_f32 v[154:155], v[184:185], s[44:45], v[154:155] op_sel_hi:[1,0,1]
	v_pk_fma_f32 v[152:153], v[190:191], s[44:45], v[152:153] op_sel_hi:[1,0,1]
	v_pk_fma_f32 v[150:151], v[188:189], s[44:45], v[150:151] op_sel_hi:[1,0,1]
	v_pk_fma_f32 v[148:149], v[194:195], s[44:45], v[148:149] op_sel_hi:[1,0,1]
	v_pk_fma_f32 v[146:147], v[192:193], s[44:45], v[146:147] op_sel_hi:[1,0,1]
	global_store_dwordx4 v[196:197], v[158:161], off
	global_store_dwordx4 v[196:197], v[154:157], off offset:16
	global_store_dwordx4 v[196:197], v[150:153], off offset:512
	global_store_dwordx4 v[196:197], v[146:149], off offset:528
	v_or_b32_e32 v182, 32, v174
	v_ashrrev_i32_e32 v183, 31, v182
	v_lshlrev_b32_e32 v184, 1, v182
	v_ashrrev_i32_e32 v185, 31, v184
	v_lshlrev_b64 v[182:183], 13, v[182:183]
	v_lshl_add_u64 v[184:185], v[184:185], 2, s[22:23]
	v_lshl_add_u64 v[182:183], s[20:21], 0, v[182:183]
	v_lshl_add_u64 v[182:183], v[182:183], 0, v[172:173]
	s_waitcnt vmcnt(7)
	v_sub_f32_e32 v149, v207, v238
	v_sub_f32_e32 v148, v206, v238
	v_sub_f32_e32 v147, v205, v238
	v_sub_f32_e32 v146, v204, v238
	s_waitcnt vmcnt(6)
	v_sub_f32_e32 v153, v211, v238
	v_sub_f32_e32 v152, v210, v238
	v_sub_f32_e32 v151, v209, v238
	v_sub_f32_e32 v150, v208, v238
	s_waitcnt vmcnt(5)
	v_sub_f32_e32 v157, v215, v238
	v_sub_f32_e32 v156, v214, v238
	v_sub_f32_e32 v155, v213, v238
	v_sub_f32_e32 v154, v212, v238
	s_waitcnt vmcnt(4)
	v_sub_f32_e32 v161, v219, v238
	v_sub_f32_e32 v160, v218, v238
	v_sub_f32_e32 v159, v217, v238
	v_sub_f32_e32 v158, v216, v238
	v_pk_mul_f32 v[146:147], v[238:239], v[146:147] op_sel:[1,0]
	v_pk_mul_f32 v[148:149], v[238:239], v[148:149] op_sel:[1,0]
	v_pk_mul_f32 v[150:151], v[238:239], v[150:151] op_sel:[1,0]
	v_pk_mul_f32 v[152:153], v[238:239], v[152:153] op_sel:[1,0]
	v_pk_mul_f32 v[154:155], v[238:239], v[154:155] op_sel:[1,0]
	v_pk_mul_f32 v[156:157], v[238:239], v[156:157] op_sel:[1,0]
	v_pk_mul_f32 v[158:159], v[238:239], v[158:159] op_sel:[1,0]
	v_pk_mul_f32 v[160:161], v[238:239], v[160:161] op_sel:[1,0]
	global_load_dwordx2 v[238:239], v[184:185], off
	global_load_dwordx4 v[204:207], v[182:183], off
	global_load_dwordx4 v[208:211], v[182:183], off offset:16
	global_load_dwordx4 v[212:215], v[182:183], off offset:512
	global_load_dwordx4 v[216:219], v[182:183], off offset:528
	v_pk_fma_f32 v[148:149], v[132:133], v[148:149], v[120:121]
	v_pk_fma_f32 v[146:147], v[130:131], v[146:147], v[118:119]
	v_pk_fma_f32 v[152:153], v[116:117], v[152:153], v[136:137]
	v_pk_fma_f32 v[150:151], v[114:115], v[150:151], v[134:135]
	v_pk_fma_f32 v[156:157], v[140:141], v[156:157], v[128:129]
	v_pk_fma_f32 v[154:155], v[138:139], v[154:155], v[126:127]
	v_pk_fma_f32 v[160:161], v[124:125], v[160:161], v[144:145]
	v_pk_fma_f32 v[158:159], v[122:123], v[158:159], v[142:143]
	v_pk_fma_f32 v[112:113], v[148:149], s[44:45], v[112:113] op_sel_hi:[1,0,1]
	v_pk_fma_f32 v[110:111], v[146:147], s[44:45], v[110:111] op_sel_hi:[1,0,1]
	v_pk_fma_f32 v[108:109], v[152:153], s[44:45], v[108:109] op_sel_hi:[1,0,1]
	v_pk_fma_f32 v[106:107], v[150:151], s[44:45], v[106:107] op_sel_hi:[1,0,1]
	v_pk_fma_f32 v[104:105], v[156:157], s[44:45], v[104:105] op_sel_hi:[1,0,1]
	v_pk_fma_f32 v[102:103], v[154:155], s[44:45], v[102:103] op_sel_hi:[1,0,1]
	v_pk_fma_f32 v[100:101], v[160:161], s[44:45], v[100:101] op_sel_hi:[1,0,1]
	v_pk_fma_f32 v[98:99], v[158:159], s[44:45], v[98:99] op_sel_hi:[1,0,1]
	global_store_dwordx4 v[200:201], v[110:113], off
	global_store_dwordx4 v[200:201], v[106:109], off offset:16
	global_store_dwordx4 v[200:201], v[102:105], off offset:512
	global_store_dwordx4 v[200:201], v[98:101], off offset:528
	v_or_b32_e32 v148, 48, v174
	v_ashrrev_i32_e32 v149, 31, v148
	v_lshlrev_b32_e32 v150, 1, v148
	v_ashrrev_i32_e32 v151, 31, v150
	v_lshlrev_b64 v[148:149], 13, v[148:149]
	v_lshl_add_u64 v[150:151], v[150:151], 2, s[22:23]
	v_lshl_add_u64 v[148:149], s[20:21], 0, v[148:149]
	v_lshl_add_u64 v[148:149], v[148:149], 0, v[172:173]
	s_waitcnt vmcnt(7)
	v_sub_f32_e32 v101, v207, v238
	v_sub_f32_e32 v100, v206, v238
	v_sub_f32_e32 v99, v205, v238
	v_sub_f32_e32 v98, v204, v238
	s_waitcnt vmcnt(6)
	v_sub_f32_e32 v105, v211, v238
	v_sub_f32_e32 v104, v210, v238
	v_sub_f32_e32 v103, v209, v238
	v_sub_f32_e32 v102, v208, v238
	s_waitcnt vmcnt(5)
	v_sub_f32_e32 v109, v215, v238
	v_sub_f32_e32 v108, v214, v238
	v_sub_f32_e32 v107, v213, v238
	v_sub_f32_e32 v106, v212, v238
	s_waitcnt vmcnt(4)
	v_sub_f32_e32 v113, v219, v238
	v_sub_f32_e32 v112, v218, v238
	v_sub_f32_e32 v111, v217, v238
	v_sub_f32_e32 v110, v216, v238
	v_pk_mul_f32 v[98:99], v[238:239], v[98:99] op_sel:[1,0]
	v_pk_mul_f32 v[100:101], v[238:239], v[100:101] op_sel:[1,0]
	v_pk_mul_f32 v[102:103], v[238:239], v[102:103] op_sel:[1,0]
	v_pk_mul_f32 v[104:105], v[238:239], v[104:105] op_sel:[1,0]
	v_pk_mul_f32 v[106:107], v[238:239], v[106:107] op_sel:[1,0]
	v_pk_mul_f32 v[108:109], v[238:239], v[108:109] op_sel:[1,0]
	v_pk_mul_f32 v[110:111], v[238:239], v[110:111] op_sel:[1,0]
	v_pk_mul_f32 v[112:113], v[238:239], v[112:113] op_sel:[1,0]
	global_load_dwordx2 v[238:239], v[150:151], off
	global_load_dwordx4 v[204:207], v[148:149], off
	global_load_dwordx4 v[208:211], v[148:149], off offset:16
	global_load_dwordx4 v[212:215], v[148:149], off offset:512
	global_load_dwordx4 v[216:219], v[148:149], off offset:528
	v_pk_fma_f32 v[100:101], v[132:133], v[100:101], v[120:121]
	v_pk_fma_f32 v[98:99], v[130:131], v[98:99], v[118:119]
	v_pk_fma_f32 v[104:105], v[116:117], v[104:105], v[136:137]
	v_pk_fma_f32 v[102:103], v[114:115], v[102:103], v[134:135]
	v_pk_fma_f32 v[108:109], v[140:141], v[108:109], v[128:129]
	v_pk_fma_f32 v[106:107], v[138:139], v[106:107], v[126:127]
	v_pk_fma_f32 v[112:113], v[124:125], v[112:113], v[144:145]
	v_pk_fma_f32 v[110:111], v[122:123], v[110:111], v[142:143]
	v_pk_fma_f32 v[96:97], v[100:101], s[44:45], v[96:97] op_sel_hi:[1,0,1]
	v_pk_fma_f32 v[94:95], v[98:99], s[44:45], v[94:95] op_sel_hi:[1,0,1]
	v_pk_fma_f32 v[92:93], v[104:105], s[44:45], v[92:93] op_sel_hi:[1,0,1]
	v_pk_fma_f32 v[90:91], v[102:103], s[44:45], v[90:91] op_sel_hi:[1,0,1]
	v_pk_fma_f32 v[88:89], v[108:109], s[44:45], v[88:89] op_sel_hi:[1,0,1]
	v_pk_fma_f32 v[86:87], v[106:107], s[44:45], v[86:87] op_sel_hi:[1,0,1]
	v_pk_fma_f32 v[84:85], v[112:113], s[44:45], v[84:85] op_sel_hi:[1,0,1]
	v_pk_fma_f32 v[82:83], v[110:111], s[44:45], v[82:83] op_sel_hi:[1,0,1]
	global_store_dwordx4 v[182:183], v[94:97], off
	global_store_dwordx4 v[182:183], v[90:93], off offset:16
	global_store_dwordx4 v[182:183], v[86:89], off offset:512
	global_store_dwordx4 v[182:183], v[82:85], off offset:528
	v_add_u32_e32 v100, 0x80, v174
	v_ashrrev_i32_e32 v101, 31, v100
	v_lshlrev_b32_e32 v102, 1, v100
	v_ashrrev_i32_e32 v103, 31, v102
	v_lshlrev_b64 v[100:101], 13, v[100:101]
	v_lshl_add_u64 v[102:103], v[102:103], 2, s[22:23]
	v_lshl_add_u64 v[100:101], s[20:21], 0, v[100:101]
	v_lshl_add_u64 v[100:101], v[100:101], 0, v[172:173]
	s_waitcnt vmcnt(7)
	v_sub_f32_e32 v85, v207, v238
	v_sub_f32_e32 v84, v206, v238
	v_sub_f32_e32 v83, v205, v238
	v_sub_f32_e32 v82, v204, v238
	s_waitcnt vmcnt(6)
	v_sub_f32_e32 v89, v211, v238
	v_sub_f32_e32 v88, v210, v238
	v_sub_f32_e32 v87, v209, v238
	v_sub_f32_e32 v86, v208, v238
	s_waitcnt vmcnt(5)
	v_sub_f32_e32 v93, v215, v238
	v_sub_f32_e32 v92, v214, v238
	v_sub_f32_e32 v91, v213, v238
	v_sub_f32_e32 v90, v212, v238
	s_waitcnt vmcnt(4)
	v_sub_f32_e32 v97, v219, v238
	v_sub_f32_e32 v96, v218, v238
	v_sub_f32_e32 v95, v217, v238
	v_sub_f32_e32 v94, v216, v238
	v_pk_mul_f32 v[82:83], v[238:239], v[82:83] op_sel:[1,0]
	v_pk_mul_f32 v[84:85], v[238:239], v[84:85] op_sel:[1,0]
	v_pk_mul_f32 v[86:87], v[238:239], v[86:87] op_sel:[1,0]
	v_pk_mul_f32 v[88:89], v[238:239], v[88:89] op_sel:[1,0]
	v_pk_mul_f32 v[90:91], v[238:239], v[90:91] op_sel:[1,0]
	v_pk_mul_f32 v[92:93], v[238:239], v[92:93] op_sel:[1,0]
	v_pk_mul_f32 v[94:95], v[238:239], v[94:95] op_sel:[1,0]
	v_pk_mul_f32 v[96:97], v[238:239], v[96:97] op_sel:[1,0]
	global_load_dwordx2 v[238:239], v[102:103], off
	global_load_dwordx4 v[204:207], v[100:101], off
	global_load_dwordx4 v[208:211], v[100:101], off offset:16
	global_load_dwordx4 v[212:215], v[100:101], off offset:512
	global_load_dwordx4 v[216:219], v[100:101], off offset:528
	v_pk_fma_f32 v[84:85], v[132:133], v[84:85], v[120:121]
	v_pk_fma_f32 v[82:83], v[130:131], v[82:83], v[118:119]
	v_pk_fma_f32 v[88:89], v[116:117], v[88:89], v[136:137]
	v_pk_fma_f32 v[86:87], v[114:115], v[86:87], v[134:135]
	v_pk_fma_f32 v[92:93], v[140:141], v[92:93], v[128:129]
	v_pk_fma_f32 v[90:91], v[138:139], v[90:91], v[126:127]
	v_pk_fma_f32 v[96:97], v[124:125], v[96:97], v[144:145]
	v_pk_fma_f32 v[94:95], v[122:123], v[94:95], v[142:143]
	v_pk_fma_f32 v[80:81], v[84:85], s[44:45], v[80:81] op_sel_hi:[1,0,1]
	v_pk_fma_f32 v[78:79], v[82:83], s[44:45], v[78:79] op_sel_hi:[1,0,1]
	v_pk_fma_f32 v[76:77], v[88:89], s[44:45], v[76:77] op_sel_hi:[1,0,1]
	v_pk_fma_f32 v[74:75], v[86:87], s[44:45], v[74:75] op_sel_hi:[1,0,1]
	v_pk_fma_f32 v[72:73], v[92:93], s[44:45], v[72:73] op_sel_hi:[1,0,1]
	v_pk_fma_f32 v[70:71], v[90:91], s[44:45], v[70:71] op_sel_hi:[1,0,1]
	v_pk_fma_f32 v[68:69], v[96:97], s[44:45], v[68:69] op_sel_hi:[1,0,1]
	v_pk_fma_f32 v[66:67], v[94:95], s[44:45], v[66:67] op_sel_hi:[1,0,1]
	global_store_dwordx4 v[148:149], v[78:81], off
	global_store_dwordx4 v[148:149], v[74:77], off offset:16
	global_store_dwordx4 v[148:149], v[70:73], off offset:512
	global_store_dwordx4 v[148:149], v[66:69], off offset:528
	v_add_u32_e32 v84, 0x90, v174
	v_ashrrev_i32_e32 v85, 31, v84
	v_lshlrev_b32_e32 v86, 1, v84
	v_ashrrev_i32_e32 v87, 31, v86
	v_lshlrev_b64 v[84:85], 13, v[84:85]
	v_lshl_add_u64 v[86:87], v[86:87], 2, s[22:23]
	v_lshl_add_u64 v[84:85], s[20:21], 0, v[84:85]
	v_lshl_add_u64 v[84:85], v[84:85], 0, v[172:173]
	s_waitcnt vmcnt(7)
	v_sub_f32_e32 v69, v207, v238
	v_sub_f32_e32 v68, v206, v238
	v_sub_f32_e32 v67, v205, v238
	v_sub_f32_e32 v66, v204, v238
	s_waitcnt vmcnt(6)
	v_sub_f32_e32 v73, v211, v238
	v_sub_f32_e32 v72, v210, v238
	v_sub_f32_e32 v71, v209, v238
	v_sub_f32_e32 v70, v208, v238
	s_waitcnt vmcnt(5)
	v_sub_f32_e32 v77, v215, v238
	v_sub_f32_e32 v76, v214, v238
	v_sub_f32_e32 v75, v213, v238
	v_sub_f32_e32 v74, v212, v238
	s_waitcnt vmcnt(4)
	v_sub_f32_e32 v81, v219, v238
	v_sub_f32_e32 v80, v218, v238
	v_sub_f32_e32 v79, v217, v238
	v_sub_f32_e32 v78, v216, v238
	v_pk_mul_f32 v[66:67], v[238:239], v[66:67] op_sel:[1,0]
	v_pk_mul_f32 v[68:69], v[238:239], v[68:69] op_sel:[1,0]
	v_pk_mul_f32 v[70:71], v[238:239], v[70:71] op_sel:[1,0]
	v_pk_mul_f32 v[72:73], v[238:239], v[72:73] op_sel:[1,0]
	v_pk_mul_f32 v[74:75], v[238:239], v[74:75] op_sel:[1,0]
	v_pk_mul_f32 v[76:77], v[238:239], v[76:77] op_sel:[1,0]
	v_pk_mul_f32 v[78:79], v[238:239], v[78:79] op_sel:[1,0]
	v_pk_mul_f32 v[80:81], v[238:239], v[80:81] op_sel:[1,0]
	global_load_dwordx2 v[238:239], v[86:87], off
	global_load_dwordx4 v[204:207], v[84:85], off
	global_load_dwordx4 v[208:211], v[84:85], off offset:16
	global_load_dwordx4 v[212:215], v[84:85], off offset:512
	global_load_dwordx4 v[216:219], v[84:85], off offset:528
	v_pk_fma_f32 v[68:69], v[132:133], v[68:69], v[120:121]
	v_pk_fma_f32 v[66:67], v[130:131], v[66:67], v[118:119]
	v_pk_fma_f32 v[72:73], v[116:117], v[72:73], v[136:137]
	v_pk_fma_f32 v[70:71], v[114:115], v[70:71], v[134:135]
	v_pk_fma_f32 v[76:77], v[140:141], v[76:77], v[128:129]
	v_pk_fma_f32 v[74:75], v[138:139], v[74:75], v[126:127]
	v_pk_fma_f32 v[80:81], v[124:125], v[80:81], v[144:145]
	v_pk_fma_f32 v[78:79], v[122:123], v[78:79], v[142:143]
	v_pk_fma_f32 v[64:65], v[68:69], s[44:45], v[64:65] op_sel_hi:[1,0,1]
	v_pk_fma_f32 v[62:63], v[66:67], s[44:45], v[62:63] op_sel_hi:[1,0,1]
	v_pk_fma_f32 v[60:61], v[72:73], s[44:45], v[60:61] op_sel_hi:[1,0,1]
	v_pk_fma_f32 v[58:59], v[70:71], s[44:45], v[58:59] op_sel_hi:[1,0,1]
	v_pk_fma_f32 v[56:57], v[76:77], s[44:45], v[56:57] op_sel_hi:[1,0,1]
	v_pk_fma_f32 v[54:55], v[74:75], s[44:45], v[54:55] op_sel_hi:[1,0,1]
	v_pk_fma_f32 v[52:53], v[80:81], s[44:45], v[52:53] op_sel_hi:[1,0,1]
	v_pk_fma_f32 v[50:51], v[78:79], s[44:45], v[50:51] op_sel_hi:[1,0,1]
	global_store_dwordx4 v[100:101], v[62:65], off
	global_store_dwordx4 v[100:101], v[58:61], off offset:16
	global_store_dwordx4 v[100:101], v[54:57], off offset:512
	global_store_dwordx4 v[100:101], v[50:53], off offset:528
	v_add_u32_e32 v68, 0xa0, v174
	v_ashrrev_i32_e32 v69, 31, v68
	v_lshlrev_b32_e32 v70, 1, v68
	v_ashrrev_i32_e32 v71, 31, v70
	v_lshlrev_b64 v[68:69], 13, v[68:69]
	v_lshl_add_u64 v[70:71], v[70:71], 2, s[22:23]
	v_lshl_add_u64 v[68:69], s[20:21], 0, v[68:69]
	v_lshl_add_u64 v[68:69], v[68:69], 0, v[172:173]
	s_waitcnt vmcnt(7)
	v_sub_f32_e32 v53, v207, v238
	v_sub_f32_e32 v52, v206, v238
	v_sub_f32_e32 v51, v205, v238
	v_sub_f32_e32 v50, v204, v238
	s_waitcnt vmcnt(6)
	v_sub_f32_e32 v57, v211, v238
	v_sub_f32_e32 v56, v210, v238
	v_sub_f32_e32 v55, v209, v238
	v_sub_f32_e32 v54, v208, v238
	s_waitcnt vmcnt(5)
	v_sub_f32_e32 v61, v215, v238
	v_sub_f32_e32 v60, v214, v238
	v_sub_f32_e32 v59, v213, v238
	v_sub_f32_e32 v58, v212, v238
	s_waitcnt vmcnt(4)
	v_sub_f32_e32 v65, v219, v238
	v_sub_f32_e32 v64, v218, v238
	v_sub_f32_e32 v63, v217, v238
	v_sub_f32_e32 v62, v216, v238
	v_pk_mul_f32 v[50:51], v[238:239], v[50:51] op_sel:[1,0]
	v_pk_mul_f32 v[52:53], v[238:239], v[52:53] op_sel:[1,0]
	v_pk_mul_f32 v[54:55], v[238:239], v[54:55] op_sel:[1,0]
	v_pk_mul_f32 v[56:57], v[238:239], v[56:57] op_sel:[1,0]
	v_pk_mul_f32 v[58:59], v[238:239], v[58:59] op_sel:[1,0]
	v_pk_mul_f32 v[60:61], v[238:239], v[60:61] op_sel:[1,0]
	v_pk_mul_f32 v[62:63], v[238:239], v[62:63] op_sel:[1,0]
	v_pk_mul_f32 v[64:65], v[238:239], v[64:65] op_sel:[1,0]
	global_load_dwordx2 v[238:239], v[70:71], off
	global_load_dwordx4 v[204:207], v[68:69], off
	global_load_dwordx4 v[208:211], v[68:69], off offset:16
	global_load_dwordx4 v[212:215], v[68:69], off offset:512
	global_load_dwordx4 v[216:219], v[68:69], off offset:528
	v_pk_fma_f32 v[52:53], v[132:133], v[52:53], v[120:121]
	v_pk_fma_f32 v[50:51], v[130:131], v[50:51], v[118:119]
	v_pk_fma_f32 v[56:57], v[116:117], v[56:57], v[136:137]
	v_pk_fma_f32 v[54:55], v[114:115], v[54:55], v[134:135]
	v_pk_fma_f32 v[60:61], v[140:141], v[60:61], v[128:129]
	v_pk_fma_f32 v[58:59], v[138:139], v[58:59], v[126:127]
	v_pk_fma_f32 v[64:65], v[124:125], v[64:65], v[144:145]
	v_pk_fma_f32 v[62:63], v[122:123], v[62:63], v[142:143]
	v_pk_fma_f32 v[48:49], v[52:53], s[44:45], v[48:49] op_sel_hi:[1,0,1]
	v_pk_fma_f32 v[46:47], v[50:51], s[44:45], v[46:47] op_sel_hi:[1,0,1]
	v_pk_fma_f32 v[44:45], v[56:57], s[44:45], v[44:45] op_sel_hi:[1,0,1]
	v_pk_fma_f32 v[42:43], v[54:55], s[44:45], v[42:43] op_sel_hi:[1,0,1]
	v_pk_fma_f32 v[40:41], v[60:61], s[44:45], v[40:41] op_sel_hi:[1,0,1]
	v_pk_fma_f32 v[38:39], v[58:59], s[44:45], v[38:39] op_sel_hi:[1,0,1]
	v_pk_fma_f32 v[36:37], v[64:65], s[44:45], v[36:37] op_sel_hi:[1,0,1]
	v_pk_fma_f32 v[34:35], v[62:63], s[44:45], v[34:35] op_sel_hi:[1,0,1]
	global_store_dwordx4 v[84:85], v[46:49], off
	global_store_dwordx4 v[84:85], v[42:45], off offset:16
	global_store_dwordx4 v[84:85], v[38:41], off offset:512
	global_store_dwordx4 v[84:85], v[34:37], off offset:528
	v_add_u32_e32 v52, 0xb0, v174
	v_ashrrev_i32_e32 v53, 31, v52
	v_lshlrev_b32_e32 v54, 1, v52
	v_ashrrev_i32_e32 v55, 31, v54
	v_lshlrev_b64 v[52:53], 13, v[52:53]
	v_lshl_add_u64 v[54:55], v[54:55], 2, s[22:23]
	v_lshl_add_u64 v[52:53], s[20:21], 0, v[52:53]
	v_lshl_add_u64 v[52:53], v[52:53], 0, v[172:173]
	s_waitcnt vmcnt(7)
	v_sub_f32_e32 v37, v207, v238
	v_sub_f32_e32 v36, v206, v238
	v_sub_f32_e32 v35, v205, v238
	v_sub_f32_e32 v34, v204, v238
	s_waitcnt vmcnt(6)
	v_sub_f32_e32 v41, v211, v238
	v_sub_f32_e32 v40, v210, v238
	v_sub_f32_e32 v39, v209, v238
	v_sub_f32_e32 v38, v208, v238
	s_waitcnt vmcnt(5)
	v_sub_f32_e32 v45, v215, v238
	v_sub_f32_e32 v44, v214, v238
	v_sub_f32_e32 v43, v213, v238
	v_sub_f32_e32 v42, v212, v238
	s_waitcnt vmcnt(4)
	v_sub_f32_e32 v49, v219, v238
	v_sub_f32_e32 v48, v218, v238
	v_sub_f32_e32 v47, v217, v238
	v_sub_f32_e32 v46, v216, v238
	v_pk_mul_f32 v[34:35], v[238:239], v[34:35] op_sel:[1,0]
	v_pk_mul_f32 v[36:37], v[238:239], v[36:37] op_sel:[1,0]
	v_pk_mul_f32 v[38:39], v[238:239], v[38:39] op_sel:[1,0]
	v_pk_mul_f32 v[40:41], v[238:239], v[40:41] op_sel:[1,0]
	v_pk_mul_f32 v[42:43], v[238:239], v[42:43] op_sel:[1,0]
	v_pk_mul_f32 v[44:45], v[238:239], v[44:45] op_sel:[1,0]
	v_pk_mul_f32 v[46:47], v[238:239], v[46:47] op_sel:[1,0]
	v_pk_mul_f32 v[48:49], v[238:239], v[48:49] op_sel:[1,0]
	global_load_dwordx2 v[238:239], v[54:55], off
	global_load_dwordx4 v[204:207], v[52:53], off
	global_load_dwordx4 v[208:211], v[52:53], off offset:16
	global_load_dwordx4 v[212:215], v[52:53], off offset:512
	global_load_dwordx4 v[216:219], v[52:53], off offset:528
	v_pk_fma_f32 v[36:37], v[132:133], v[36:37], v[120:121]
	v_pk_fma_f32 v[34:35], v[130:131], v[34:35], v[118:119]
	v_pk_fma_f32 v[40:41], v[116:117], v[40:41], v[136:137]
	v_pk_fma_f32 v[38:39], v[114:115], v[38:39], v[134:135]
	v_pk_fma_f32 v[44:45], v[140:141], v[44:45], v[128:129]
	v_pk_fma_f32 v[42:43], v[138:139], v[42:43], v[126:127]
	v_pk_fma_f32 v[48:49], v[124:125], v[48:49], v[144:145]
	v_pk_fma_f32 v[46:47], v[122:123], v[46:47], v[142:143]
	v_pk_fma_f32 v[32:33], v[36:37], s[44:45], v[32:33] op_sel_hi:[1,0,1]
	v_pk_fma_f32 v[30:31], v[34:35], s[44:45], v[30:31] op_sel_hi:[1,0,1]
	v_pk_fma_f32 v[28:29], v[40:41], s[44:45], v[28:29] op_sel_hi:[1,0,1]
	v_pk_fma_f32 v[26:27], v[38:39], s[44:45], v[26:27] op_sel_hi:[1,0,1]
	v_pk_fma_f32 v[24:25], v[44:45], s[44:45], v[24:25] op_sel_hi:[1,0,1]
	v_pk_fma_f32 v[22:23], v[42:43], s[44:45], v[22:23] op_sel_hi:[1,0,1]
	v_pk_fma_f32 v[20:21], v[48:49], s[44:45], v[20:21] op_sel_hi:[1,0,1]
	v_pk_fma_f32 v[18:19], v[46:47], s[44:45], v[18:19] op_sel_hi:[1,0,1]
	global_store_dwordx4 v[68:69], v[30:33], off
	global_store_dwordx4 v[68:69], v[26:29], off offset:16
	global_store_dwordx4 v[68:69], v[22:25], off offset:512
	global_store_dwordx4 v[68:69], v[18:21], off offset:528
	s_waitcnt vmcnt(7)
	v_sub_f32_e32 v21, v207, v238
	v_sub_f32_e32 v20, v206, v238
	v_sub_f32_e32 v19, v205, v238
	v_sub_f32_e32 v18, v204, v238
	s_waitcnt vmcnt(6)
	v_sub_f32_e32 v25, v211, v238
	v_sub_f32_e32 v24, v210, v238
	v_sub_f32_e32 v23, v209, v238
	v_sub_f32_e32 v22, v208, v238
	s_waitcnt vmcnt(5)
	v_sub_f32_e32 v29, v215, v238
	v_sub_f32_e32 v28, v214, v238
	v_sub_f32_e32 v27, v213, v238
	v_sub_f32_e32 v26, v212, v238
	s_waitcnt vmcnt(4)
	v_sub_f32_e32 v33, v219, v238
	v_sub_f32_e32 v32, v218, v238
	v_sub_f32_e32 v31, v217, v238
	v_sub_f32_e32 v30, v216, v238
	v_pk_mul_f32 v[18:19], v[238:239], v[18:19] op_sel:[1,0]
	v_pk_mul_f32 v[20:21], v[238:239], v[20:21] op_sel:[1,0]
	v_pk_mul_f32 v[22:23], v[238:239], v[22:23] op_sel:[1,0]
	v_pk_mul_f32 v[24:25], v[238:239], v[24:25] op_sel:[1,0]
	v_pk_mul_f32 v[26:27], v[238:239], v[26:27] op_sel:[1,0]
	v_pk_mul_f32 v[28:29], v[238:239], v[28:29] op_sel:[1,0]
	v_pk_mul_f32 v[30:31], v[238:239], v[30:31] op_sel:[1,0]
	v_pk_mul_f32 v[32:33], v[238:239], v[32:33] op_sel:[1,0]
	v_pk_fma_f32 v[20:21], v[132:133], v[20:21], v[120:121]
	v_pk_fma_f32 v[18:19], v[130:131], v[18:19], v[118:119]
	v_pk_fma_f32 v[24:25], v[116:117], v[24:25], v[136:137]
	v_pk_fma_f32 v[22:23], v[114:115], v[22:23], v[134:135]
	v_pk_fma_f32 v[28:29], v[140:141], v[28:29], v[128:129]
	v_pk_fma_f32 v[26:27], v[138:139], v[26:27], v[126:127]
	v_pk_fma_f32 v[32:33], v[124:125], v[32:33], v[144:145]
	v_pk_fma_f32 v[30:31], v[122:123], v[30:31], v[142:143]
	v_pk_fma_f32 v[16:17], v[20:21], s[44:45], v[16:17] op_sel_hi:[1,0,1]
	v_pk_fma_f32 v[14:15], v[18:19], s[44:45], v[14:15] op_sel_hi:[1,0,1]
	v_pk_fma_f32 v[12:13], v[24:25], s[44:45], v[12:13] op_sel_hi:[1,0,1]
	v_pk_fma_f32 v[10:11], v[22:23], s[44:45], v[10:11] op_sel_hi:[1,0,1]
	v_pk_fma_f32 v[8:9], v[28:29], s[44:45], v[8:9] op_sel_hi:[1,0,1]
	v_pk_fma_f32 v[6:7], v[26:27], s[44:45], v[6:7] op_sel_hi:[1,0,1]
	v_pk_fma_f32 v[4:5], v[32:33], s[44:45], v[4:5] op_sel_hi:[1,0,1]
	v_pk_fma_f32 v[2:3], v[30:31], s[44:45], v[2:3] op_sel_hi:[1,0,1]
	global_store_dwordx4 v[52:53], v[14:17], off
	global_store_dwordx4 v[52:53], v[10:13], off offset:16
	global_store_dwordx4 v[52:53], v[6:9], off offset:512
	global_store_dwordx4 v[52:53], v[2:5], off offset:528
	s_cbranch_vccnz .LBB0_1062
	s_andn2_b64 vcc, exec, s[18:19]
	s_cbranch_vccnz .LBB0_1061
	s_barrier
	s_branch .LBB0_1061
